# grid barrier: all waiters poll the top-level arrival word (complete at nx*(episode+1)) instead of the generation word published afterwards
# speedup vs baseline: 1.0013x; 1.0013x over previous
.LBB0_37:
	s_or_b64 exec, exec, s[12:13]
	v_cvt_f32_u32_e32 v4, v2
	s_waitcnt vmcnt(0)
	v_readfirstlane_b32 s2, v3
	v_sub_u32_e32 v3, 0, v2
	v_rcp_iflag_f32_e32 v4, v4
	v_add_u32_e32 v5, s2, v1
	v_mul_f32_e32 v4, 0x4f7ffffe, v4
	v_cvt_u32_f32_e32 v4, v4
	v_mul_lo_u32 v1, v3, v4
	v_mul_hi_u32 v1, v4, v1
	v_add_u32_e32 v1, v4, v1
	v_mul_hi_u32 v1, v5, v1
	v_mul_lo_u32 v3, v1, v2
	v_sub_u32_e32 v3, v5, v3
	v_add_u32_e32 v4, 1, v1
	v_cmp_ge_u32_e32 vcc, v3, v2
	s_nop 1
	v_cndmask_b32_e32 v1, v1, v4, vcc
	v_sub_u32_e32 v4, v3, v2
	v_cndmask_b32_e32 v3, v3, v4, vcc
	v_add_u32_e32 v4, 1, v1
	v_cmp_ge_u32_e32 vcc, v3, v2
	v_add_u32_e32 v3, 1, v5
	s_nop 0
	v_cndmask_b32_e32 v1, v1, v4, vcc
	v_mul_lo_u32 v4, v2, v1
	v_add_u32_e32 v2, v4, v2
	v_cmp_ne_u32_e32 vcc, v3, v2
	s_and_saveexec_b64 s[2:3], vcc
	s_xor_b64 s[8:9], exec, s[2:3]
	s_cbranch_execz .LBB0_51
	s_waitcnt lgkmcnt(0)
	v_mad_u32_u24 v5, v0, v1, v0
	s_add_u32 s16, s40, 0x13fb3400
	s_addc_u32 s17, s41, 0
	v_mov_b32_e32 v0, 0
	global_load_dword v0, v0, s[16:17] sc1
	s_waitcnt vmcnt(0)
	v_cmp_lt_u32_e32 vcc, v0, v5
	s_and_saveexec_b64 s[12:13], vcc
	s_cbranch_execz .LBB0_50
	s_add_u32 s14, s40, 0x13fb0200
	s_addc_u32 s15, s41, 0
	s_mov_b32 s2, 1
	s_mov_b64 s[18:19], 0
	v_mov_b32_e32 v0, 0
	s_branch .LBB0_41

.LBB0_43:
	global_load_dword v2, v0, s[16:17] sc1
	s_add_i32 s2, s2, 1
	s_mov_b64 s[24:25], -1
	s_waitcnt vmcnt(0)
	v_cmp_ge_u32_e32 vcc, v2, v5
	s_orn2_b64 s[22:23], vcc, exec
	s_branch .LBB0_40

.LBB0_54:
	s_or_b64 exec, exec, s[12:13]
	v_cvt_f32_u32_e32 v3, v0
	s_waitcnt vmcnt(0)
	v_readfirstlane_b32 s2, v2
	s_add_u32 s12, s40, 0x13fb3500
	s_addc_u32 s13, s41, 0
	v_rcp_iflag_f32_e32 v3, v3
	v_add_u32_e32 v1, s2, v1
	v_add_u32_e32 v4, 1, v1
	s_mov_b64 s[14:15], -1
	v_mul_f32_e32 v2, 0x4f7ffffe, v3
	v_cvt_u32_f32_e32 v2, v2
	v_sub_u32_e32 v3, 0, v0
	v_mul_lo_u32 v3, v3, v2
	v_mul_hi_u32 v3, v2, v3
	v_add_u32_e32 v2, v2, v3
	v_mul_hi_u32 v2, v1, v2
	v_mul_lo_u32 v3, v2, v0
	v_sub_u32_e32 v1, v1, v3
	v_add_u32_e32 v5, 1, v2
	v_cmp_ge_u32_e32 vcc, v1, v0
	v_sub_u32_e32 v3, v1, v0
	s_nop 0
	v_cndmask_b32_e32 v2, v2, v5, vcc
	v_cndmask_b32_e32 v1, v1, v3, vcc
	v_add_u32_e32 v3, 1, v2
	v_cmp_ge_u32_e32 vcc, v1, v0
	s_nop 1
	v_cndmask_b32_e32 v2, v2, v3, vcc
	v_mul_lo_u32 v1, v0, v2
	v_add_u32_e32 v0, v1, v0
	v_cmp_ne_u32_e32 vcc, v4, v0
	v_mov_b32_e32 v5, v0
	v_mov_b64_e32 v[0:1], s[12:13]
	s_and_saveexec_b64 s[8:9], vcc
	s_cbranch_execz .LBB0_66
	v_mov_b32_e32 v0, 0
	global_load_dword v1, v0, s[12:13] offset:-256 sc1
	s_mov_b64 s[18:19], 0
	s_waitcnt vmcnt(0)
	v_cmp_lt_u32_e32 vcc, v1, v5
	s_and_saveexec_b64 s[16:17], vcc
	s_cbranch_execz .LBB0_65
	s_add_u32 s14, s40, 0x13fb0200
	s_addc_u32 s15, s41, 0
	s_mov_b32 s2, 1
	s_branch .LBB0_58

.LBB0_60:
	global_load_dword v1, v0, s[12:13] offset:-256 sc1
	s_add_i32 s2, s2, 1
	s_mov_b64 s[22:23], -1
	s_waitcnt vmcnt(0)
	v_cmp_ge_u32_e32 vcc, v1, v5
	s_orn2_b64 s[26:27], vcc, exec
	s_branch .LBB0_57

.LBB0_250:
	s_or_b64 exec, exec, s[14:15]
	v_cvt_f32_u32_e32 v4, v2
	s_waitcnt vmcnt(0)
	v_readfirstlane_b32 s2, v3
	v_sub_u32_e32 v3, 0, v2
	v_rcp_iflag_f32_e32 v4, v4
	v_add_u32_e32 v5, s2, v1
	v_mul_f32_e32 v4, 0x4f7ffffe, v4
	v_cvt_u32_f32_e32 v4, v4
	v_mul_lo_u32 v1, v3, v4
	v_mul_hi_u32 v1, v4, v1
	v_add_u32_e32 v1, v4, v1
	v_mul_hi_u32 v1, v5, v1
	v_mul_lo_u32 v3, v1, v2
	v_sub_u32_e32 v3, v5, v3
	v_add_u32_e32 v4, 1, v1
	v_cmp_ge_u32_e32 vcc, v3, v2
	s_nop 1
	v_cndmask_b32_e32 v1, v1, v4, vcc
	v_sub_u32_e32 v4, v3, v2
	v_cndmask_b32_e32 v3, v3, v4, vcc
	v_add_u32_e32 v4, 1, v1
	v_cmp_ge_u32_e32 vcc, v3, v2
	v_add_u32_e32 v3, 1, v5
	s_nop 0
	v_cndmask_b32_e32 v1, v1, v4, vcc
	v_mul_lo_u32 v4, v2, v1
	v_add_u32_e32 v2, v4, v2
	v_cmp_ne_u32_e32 vcc, v3, v2
	s_and_saveexec_b64 s[2:3], vcc
	s_xor_b64 s[12:13], exec, s[2:3]
	s_cbranch_execz .LBB0_264
	s_waitcnt lgkmcnt(0)
	v_mad_u32_u24 v5, v0, v1, v0
	s_add_u32 s18, s40, 0x13fb3400
	s_addc_u32 s19, s41, 0
	v_mov_b32_e32 v0, 0
	global_load_dword v0, v0, s[18:19] sc1
	s_waitcnt vmcnt(0)
	v_cmp_lt_u32_e32 vcc, v0, v5
	s_and_saveexec_b64 s[14:15], vcc
	s_cbranch_execz .LBB0_263
	s_add_u32 s16, s40, 0x13fb0200
	s_addc_u32 s17, s41, 0
	s_mov_b32 s2, 1
	s_mov_b64 s[20:21], 0
	v_mov_b32_e32 v0, 0
	s_branch .LBB0_254

.LBB0_256:
	global_load_dword v2, v0, s[18:19] sc1
	s_add_i32 s2, s2, 1
	s_mov_b64 s[26:27], -1
	s_waitcnt vmcnt(0)
	v_cmp_ge_u32_e32 vcc, v2, v5
	s_orn2_b64 s[24:25], vcc, exec
	s_branch .LBB0_253

.LBB0_267:
	s_or_b64 exec, exec, s[14:15]
	v_cvt_f32_u32_e32 v3, v0
	s_waitcnt vmcnt(0)
	v_readfirstlane_b32 s2, v2
	s_add_u32 s14, s40, 0x13fb3500
	s_addc_u32 s15, s41, 0
	v_rcp_iflag_f32_e32 v3, v3
	v_add_u32_e32 v1, s2, v1
	v_add_u32_e32 v4, 1, v1
	s_mov_b64 s[16:17], -1
	v_mul_f32_e32 v2, 0x4f7ffffe, v3
	v_cvt_u32_f32_e32 v2, v2
	v_sub_u32_e32 v3, 0, v0
	v_mul_lo_u32 v3, v3, v2
	v_mul_hi_u32 v3, v2, v3
	v_add_u32_e32 v2, v2, v3
	v_mul_hi_u32 v2, v1, v2
	v_mul_lo_u32 v3, v2, v0
	v_sub_u32_e32 v1, v1, v3
	v_add_u32_e32 v5, 1, v2
	v_cmp_ge_u32_e32 vcc, v1, v0
	v_sub_u32_e32 v3, v1, v0
	s_nop 0
	v_cndmask_b32_e32 v2, v2, v5, vcc
	v_cndmask_b32_e32 v1, v1, v3, vcc
	v_add_u32_e32 v3, 1, v2
	v_cmp_ge_u32_e32 vcc, v1, v0
	s_nop 1
	v_cndmask_b32_e32 v2, v2, v3, vcc
	v_mul_lo_u32 v1, v0, v2
	v_add_u32_e32 v0, v1, v0
	v_cmp_ne_u32_e32 vcc, v4, v0
	v_mov_b32_e32 v5, v0
	v_mov_b64_e32 v[0:1], s[14:15]
	s_and_saveexec_b64 s[12:13], vcc
	s_cbranch_execz .LBB0_279
	v_mov_b32_e32 v0, 0
	global_load_dword v1, v0, s[14:15] offset:-256 sc1
	s_mov_b64 s[20:21], 0
	s_waitcnt vmcnt(0)
	v_cmp_lt_u32_e32 vcc, v1, v5
	s_and_saveexec_b64 s[18:19], vcc
	s_cbranch_execz .LBB0_278
	s_add_u32 s16, s40, 0x13fb0200
	s_addc_u32 s17, s41, 0
	s_mov_b32 s2, 1
	s_branch .LBB0_271

.LBB0_273:
	global_load_dword v1, v0, s[14:15] offset:-256 sc1
	s_add_i32 s2, s2, 1
	s_mov_b64 s[24:25], -1
	s_waitcnt vmcnt(0)
	v_cmp_ge_u32_e32 vcc, v1, v5
	s_orn2_b64 s[28:29], vcc, exec
	s_branch .LBB0_270

.LBB0_609:
	global_load_dword v2, v0, s[16:17] sc1
	s_add_i32 s2, s2, 1
	s_mov_b64 s[26:27], -1
	s_waitcnt vmcnt(0)
	v_cmp_ge_u32_e32 vcc, v2, v5
	s_orn2_b64 s[22:23], vcc, exec
	s_branch .LBB0_606

.LBB0_626:
	global_load_dword v1, v0, s[12:13] offset:-256 sc1
	s_add_i32 s2, s2, 1
	s_mov_b64 s[22:23], -1
	s_waitcnt vmcnt(0)
	v_cmp_ge_u32_e32 vcc, v1, v5
	s_orn2_b64 s[28:29], vcc, exec
	s_branch .LBB0_623

.LBB0_761:
	global_load_dword v2, v0, s[16:17] sc1
	s_add_i32 s2, s2, 1
	s_mov_b64 s[26:27], -1
	s_waitcnt vmcnt(0)
	v_cmp_ge_u32_e32 vcc, v2, v5
	s_orn2_b64 s[24:25], vcc, exec
	s_branch .LBB0_758

.LBB0_778:
	global_load_dword v1, v0, s[12:13] offset:-256 sc1
	s_add_i32 s2, s2, 1
	s_mov_b64 s[24:25], -1
	s_waitcnt vmcnt(0)
	v_cmp_ge_u32_e32 vcc, v1, v5
	s_orn2_b64 s[28:29], vcc, exec
	s_branch .LBB0_775

.LBB0_886:
	s_or_b64 exec, exec, s[12:13]
	v_cvt_f32_u32_e32 v4, v2
	s_waitcnt vmcnt(0)
	v_readfirstlane_b32 s2, v3
	v_sub_u32_e32 v3, 0, v2
	v_rcp_iflag_f32_e32 v4, v4
	v_add_u32_e32 v5, s2, v1
	v_mul_f32_e32 v4, 0x4f7ffffe, v4
	v_cvt_u32_f32_e32 v4, v4
	v_mul_lo_u32 v1, v3, v4
	v_mul_hi_u32 v1, v4, v1
	v_add_u32_e32 v1, v4, v1
	v_mul_hi_u32 v1, v5, v1
	v_mul_lo_u32 v3, v1, v2
	v_sub_u32_e32 v3, v5, v3
	v_add_u32_e32 v4, 1, v1
	v_cmp_ge_u32_e32 vcc, v3, v2
	s_nop 1
	v_cndmask_b32_e32 v1, v1, v4, vcc
	v_sub_u32_e32 v4, v3, v2
	v_cndmask_b32_e32 v3, v3, v4, vcc
	v_add_u32_e32 v4, 1, v1
	v_cmp_ge_u32_e32 vcc, v3, v2
	v_add_u32_e32 v3, 1, v5
	s_nop 0
	v_cndmask_b32_e32 v1, v1, v4, vcc
	v_mul_lo_u32 v4, v2, v1
	v_add_u32_e32 v2, v4, v2
	v_cmp_ne_u32_e32 vcc, v3, v2
	s_and_saveexec_b64 s[2:3], vcc
	s_xor_b64 s[8:9], exec, s[2:3]
	s_cbranch_execz .LBB0_900
	s_waitcnt lgkmcnt(0)
	v_mad_u32_u24 v5, v0, v1, v0
	s_add_u32 s18, s40, 0x13fb3400
	s_addc_u32 s19, s41, 0
	v_mov_b32_e32 v0, 0
	global_load_dword v0, v0, s[18:19] sc1
	s_waitcnt vmcnt(0)
	v_cmp_lt_u32_e32 vcc, v0, v5
	s_and_saveexec_b64 s[12:13], vcc
	s_cbranch_execz .LBB0_899
	s_add_u32 s14, s40, 0x13fb0200
	s_addc_u32 s15, s41, 0
	s_mov_b32 s2, 1
	s_mov_b64 s[20:21], 0
	v_mov_b32_e32 v0, 0
	s_branch .LBB0_890

.LBB0_903:
	s_or_b64 exec, exec, s[12:13]
	v_cvt_f32_u32_e32 v3, v0
	s_waitcnt vmcnt(0)
	v_readfirstlane_b32 s2, v2
	s_add_u32 s12, s40, 0x13fb3500
	s_addc_u32 s13, s41, 0
	v_rcp_iflag_f32_e32 v3, v3
	v_add_u32_e32 v1, s2, v1
	v_add_u32_e32 v4, 1, v1
	s_mov_b64 s[14:15], -1
	v_mul_f32_e32 v2, 0x4f7ffffe, v3
	v_cvt_u32_f32_e32 v2, v2
	v_sub_u32_e32 v3, 0, v0
	v_mul_lo_u32 v3, v3, v2
	v_mul_hi_u32 v3, v2, v3
	v_add_u32_e32 v2, v2, v3
	v_mul_hi_u32 v2, v1, v2
	v_mul_lo_u32 v3, v2, v0
	v_sub_u32_e32 v1, v1, v3
	v_add_u32_e32 v5, 1, v2
	v_cmp_ge_u32_e32 vcc, v1, v0
	v_sub_u32_e32 v3, v1, v0
	s_nop 0
	v_cndmask_b32_e32 v2, v2, v5, vcc
	v_cndmask_b32_e32 v1, v1, v3, vcc
	v_add_u32_e32 v3, 1, v2
	v_cmp_ge_u32_e32 vcc, v1, v0
	s_nop 1
	v_cndmask_b32_e32 v2, v2, v3, vcc
	v_mul_lo_u32 v1, v0, v2
	v_add_u32_e32 v0, v1, v0
	v_cmp_ne_u32_e32 vcc, v4, v0
	v_mov_b32_e32 v5, v0
	v_mov_b64_e32 v[0:1], s[12:13]
	s_and_saveexec_b64 s[8:9], vcc
	s_cbranch_execz .LBB0_915
	v_mov_b32_e32 v0, 0
	global_load_dword v1, v0, s[12:13] offset:-256 sc1
	s_mov_b64 s[20:21], 0
	s_waitcnt vmcnt(0)
	v_cmp_lt_u32_e32 vcc, v1, v5
	s_and_saveexec_b64 s[18:19], vcc
	s_cbranch_execz .LBB0_914
	s_add_u32 s14, s40, 0x13fb0200
	s_addc_u32 s15, s41, 0
	s_mov_b32 s2, 1
	s_branch .LBB0_907

.LBB0_1451:
	s_or_b64 exec, exec, s[10:11]
	v_cvt_f32_u32_e32 v4, v2
	s_waitcnt vmcnt(0)
	v_readfirstlane_b32 s2, v3
	v_sub_u32_e32 v3, 0, v2
	v_rcp_iflag_f32_e32 v4, v4
	v_add_u32_e32 v5, s2, v1
	v_mul_f32_e32 v4, 0x4f7ffffe, v4
	v_cvt_u32_f32_e32 v4, v4
	v_mul_lo_u32 v1, v3, v4
	v_mul_hi_u32 v1, v4, v1
	v_add_u32_e32 v1, v4, v1
	v_mul_hi_u32 v1, v5, v1
	v_mul_lo_u32 v3, v1, v2
	v_sub_u32_e32 v3, v5, v3
	v_add_u32_e32 v4, 1, v1
	v_cmp_ge_u32_e32 vcc, v3, v2
	s_nop 1
	v_cndmask_b32_e32 v1, v1, v4, vcc
	v_sub_u32_e32 v4, v3, v2
	v_cndmask_b32_e32 v3, v3, v4, vcc
	v_add_u32_e32 v4, 1, v1
	v_cmp_ge_u32_e32 vcc, v3, v2
	v_add_u32_e32 v3, 1, v5
	s_nop 0
	v_cndmask_b32_e32 v1, v1, v4, vcc
	v_mul_lo_u32 v4, v2, v1
	v_add_u32_e32 v2, v4, v2
	v_cmp_ne_u32_e32 vcc, v3, v2
	s_and_saveexec_b64 s[2:3], vcc
	s_xor_b64 s[8:9], exec, s[2:3]
	s_cbranch_execz .LBB0_1465
	s_waitcnt lgkmcnt(0)
	v_mad_u32_u24 v5, v0, v1, v0
	s_add_u32 s14, s40, 0x13fb3400
	s_addc_u32 s15, s41, 0
	v_mov_b32_e32 v0, 0
	global_load_dword v0, v0, s[14:15] sc1
	s_waitcnt vmcnt(0)
	v_cmp_lt_u32_e32 vcc, v0, v5
	s_and_saveexec_b64 s[10:11], vcc
	s_cbranch_execz .LBB0_1464
	s_add_u32 s12, s40, 0x13fb0200
	s_addc_u32 s13, s41, 0
	s_mov_b32 s2, 1
	s_mov_b64 s[16:17], 0
	v_mov_b32_e32 v0, 0
	s_branch .LBB0_1455

.LBB0_1457:
	global_load_dword v2, v0, s[14:15] sc1
	s_add_i32 s2, s2, 1
	s_mov_b64 s[22:23], -1
	s_waitcnt vmcnt(0)
	v_cmp_ge_u32_e32 vcc, v2, v5
	s_orn2_b64 s[20:21], vcc, exec
	s_branch .LBB0_1454

.LBB0_1468:
	s_or_b64 exec, exec, s[10:11]
	v_cvt_f32_u32_e32 v3, v0
	s_waitcnt vmcnt(0)
	v_readfirstlane_b32 s2, v2
	s_add_u32 s10, s40, 0x13fb3500
	s_addc_u32 s11, s41, 0
	v_rcp_iflag_f32_e32 v3, v3
	v_add_u32_e32 v1, s2, v1
	v_add_u32_e32 v4, 1, v1
	s_mov_b64 s[12:13], -1
	v_mul_f32_e32 v2, 0x4f7ffffe, v3
	v_cvt_u32_f32_e32 v2, v2
	v_sub_u32_e32 v3, 0, v0
	v_mul_lo_u32 v3, v3, v2
	v_mul_hi_u32 v3, v2, v3
	v_add_u32_e32 v2, v2, v3
	v_mul_hi_u32 v2, v1, v2
	v_mul_lo_u32 v3, v2, v0
	v_sub_u32_e32 v1, v1, v3
	v_add_u32_e32 v5, 1, v2
	v_cmp_ge_u32_e32 vcc, v1, v0
	v_sub_u32_e32 v3, v1, v0
	s_nop 0
	v_cndmask_b32_e32 v2, v2, v5, vcc
	v_cndmask_b32_e32 v1, v1, v3, vcc
	v_add_u32_e32 v3, 1, v2
	v_cmp_ge_u32_e32 vcc, v1, v0
	s_nop 1
	v_cndmask_b32_e32 v2, v2, v3, vcc
	v_mul_lo_u32 v1, v0, v2
	v_add_u32_e32 v0, v1, v0
	v_cmp_ne_u32_e32 vcc, v4, v0
	v_mov_b32_e32 v5, v0
	v_mov_b64_e32 v[0:1], s[10:11]
	s_and_saveexec_b64 s[8:9], vcc
	s_cbranch_execz .LBB0_1480
	v_mov_b32_e32 v0, 0
	global_load_dword v1, v0, s[10:11] offset:-256 sc1
	s_mov_b64 s[16:17], 0
	s_waitcnt vmcnt(0)
	v_cmp_lt_u32_e32 vcc, v1, v5
	s_and_saveexec_b64 s[14:15], vcc
	s_cbranch_execz .LBB0_1479
	s_add_u32 s12, s40, 0x13fb0200
	s_addc_u32 s13, s41, 0
	s_mov_b32 s2, 1
	s_branch .LBB0_1472

.LBB0_1474:
	global_load_dword v1, v0, s[10:11] offset:-256 sc1
	s_add_i32 s2, s2, 1
	s_mov_b64 s[20:21], -1
	s_waitcnt vmcnt(0)
	v_cmp_ge_u32_e32 vcc, v1, v5
	s_orn2_b64 s[24:25], vcc, exec
	s_branch .LBB0_1471
